# stack: permlane-swap reductions + exp(b_last) published once per channel + conflict-free g1 tile layout (all bit-identical transformations in the GLA phases)
# baseline (speedup 1.0000x reference)
.LBB0_502:
	s_add_u32 s50, s53, s46
	s_addc_u32 s51, s77, s47
	s_add_u32 s31, s43, s46
	s_addc_u32 s48, s52, s47
	s_add_u32 s80, s31, s76
	s_addc_u32 s81, s48, 0
	s_and_b32 s79, s78, 1
	s_cmp_eq_u32 s79, 0
	s_cselect_b64 s[48:49], -1, 0
	s_and_b64 s[82:83], s[48:49], exec
	s_cselect_b32 s31, 0xf0, s67
	v_and_b32_e32 v1, 63, v154
	v_lshl_add_u32 v1, v1, 2, s31
	ds_read2st64_b32 v[74:75], v1 offset1:1
	v_lshl_add_u64 v[76:77], s[50:51], 0, v[112:113]
	ds_read2st64_b32 v[82:83], v1 offset0:4 offset1:5
	global_load_dwordx4 v[94:97], v[76:77], off
	global_load_dwordx4 v[98:101], v[76:77], off offset:1024
	ds_read2st64_b32 v[108:109], v1 offset0:2 offset1:3
	v_lshl_add_u64 v[84:85], s[80:81], 0, v[114:115]
	s_mov_b32 s31, 0x3d800000
	s_waitcnt vmcnt(6) lgkmcnt(2)
	v_mfma_f32_16x16x4_f32 v[70:73], v74, v102, 0
	v_add_co_u32_e32 v74, vcc, s63, v76
	s_waitcnt vmcnt(5)
	v_mfma_f32_16x16x4_f32 v[70:73], v75, v103, v[70:73]
	v_addc_co_u32_e32 v75, vcc, 0, v77, vcc
	global_load_dwordx4 v[86:89], v[74:75], off
	global_load_dwordx4 v[90:93], v[74:75], off offset:1024
	v_add_co_u32_e32 v74, vcc, s64, v84
	s_nop 1
	v_addc_co_u32_e32 v75, vcc, 0, v85, vcc
	s_waitcnt vmcnt(6) lgkmcnt(0)
	v_mfma_f32_16x16x4_f32 v[160:163], v108, v104, v[70:73]
	v_add_co_u32_e32 v168, vcc, s63, v84
	global_load_dwordx4 v[70:73], v[84:85], off
	s_nop 0
	global_load_dwordx4 v[74:77], v[74:75], off
	v_addc_co_u32_e32 v169, vcc, 0, v85, vcc
	v_mfma_f32_16x16x4_f32 v[78:81], v82, v102, 0
	v_add_co_u32_e32 v82, vcc, s65, v84
	s_waitcnt vmcnt(7)
	v_mfma_f32_16x16x4_f32 v[160:163], v109, v105, v[160:163]
	v_mfma_f32_16x16x4_f32 v[164:167], v83, v103, v[78:81]
	v_addc_co_u32_e32 v83, vcc, 0, v85, vcc
	s_nop 4
	global_load_dwordx4 v[78:81], v[168:169], off
	s_nop 0
	global_load_dwordx4 v[82:85], v[82:83], off
	ds_read2st64_b32 v[168:169], v1 offset0:6 offset1:7
	s_waitcnt vmcnt(8)
	v_add_f32_e32 v107, v106, v160
	v_min_f32_e32 v170, 0, v107
	v_mul_f32_e64 v107, |v107|, s68
	v_exp_f32_e32 v107, v107
	v_add_f32_e32 v108, v106, v161
	v_add_f32_e32 v109, v106, v162
	v_mul_f32_e64 v160, |v108|, s68
	v_mul_f32_e64 v161, |v109|, s68
	v_exp_f32_e32 v160, v160
	v_exp_f32_e32 v161, v161
	v_add_f32_e32 v107, 1.0, v107
	v_log_f32_e32 v107, v107
	s_waitcnt lgkmcnt(0)
	v_mfma_f32_16x16x4_f32 v[164:167], v168, v104, v[164:167]
	v_add_f32_e32 v160, 1.0, v160
	v_add_f32_e32 v161, 1.0, v161
	v_log_f32_e32 v160, v160
	v_fmac_f32_e32 v170, 0xbf317218, v107
	v_log_f32_e32 v107, v161
	v_min_f32_e32 v171, 0, v108
	v_min_f32_e32 v172, 0, v109
	v_fmac_f32_e32 v171, 0xbf317218, v160
	v_fmac_f32_e32 v172, 0xbf317218, v107
	v_add_f32_e32 v107, v106, v163
	v_mfma_f32_16x16x4_f32 v[160:163], v169, v105, v[164:167]
	v_mul_f32_e64 v108, |v107|, s68
	v_exp_f32_e32 v168, v108
	v_min_f32_e32 v107, 0, v107
	v_add_f32_e32 v165, 1.0, v168
	v_log_f32_e32 v165, v165
	s_nop 4
	v_add_f32_e32 v160, v106, v160
	v_mul_f32_e64 v108, |v160|, s68
	v_exp_f32_e32 v164, v108
	ds_read2st64_b32 v[108:109], v1 offset0:8 offset1:9
	v_min_f32_e32 v173, 0, v160
	v_fmac_f32_e32 v107, 0xbf317218, v165
	v_add_f32_e32 v164, 1.0, v164
	v_log_f32_e32 v164, v164
	ds_read2st64_b32 v[168:169], v1 offset0:10 offset1:11
	v_add_f32_e32 v174, v106, v162
	v_add_f32_e32 v176, v106, v163
	v_fmac_f32_e32 v173, 0xbf317218, v164
	s_waitcnt lgkmcnt(1)
	v_mfma_f32_16x16x4_f32 v[164:167], v108, v102, 0
	v_add_f32_e32 v108, v106, v161
	v_mul_f32_e64 v160, |v108|, s68
	v_mul_f32_e64 v161, |v174|, s68
	v_exp_f32_e32 v160, v160
	v_exp_f32_e32 v161, v161
	v_min_f32_e32 v175, 0, v108
	v_mul_f32_e64 v177, |v176|, s68
	v_mfma_f32_16x16x4_f32 v[164:167], v109, v103, v[164:167]
	v_add_f32_e32 v108, 1.0, v160
	v_add_f32_e32 v109, 1.0, v161
	v_log_f32_e32 v108, v108
	v_log_f32_e32 v109, v109
	v_min_f32_e32 v174, 0, v174
	v_min_f32_e32 v176, 0, v176
	v_fmac_f32_e32 v175, 0xbf317218, v108
	s_waitcnt lgkmcnt(0)
	v_mfma_f32_16x16x4_f32 v[160:163], v168, v104, v[164:167]
	s_nop 0
	v_exp_f32_e32 v164, v177
	v_fmac_f32_e32 v174, 0xbf317218, v109
	v_add_f32_e32 v108, 1.0, v164
	v_log_f32_e32 v164, v108
	ds_read2st64_b32 v[108:109], v1 offset0:12 offset1:13
	v_mfma_f32_16x16x4_f32 v[160:163], v169, v105, v[160:163]
	v_fmac_f32_e32 v176, 0xbf317218, v164
	s_nop 8
	v_add_f32_e32 v160, v106, v160
	v_mul_f32_e64 v164, |v160|, s68
	v_exp_f32_e32 v168, v164
	s_waitcnt lgkmcnt(0)
	v_mfma_f32_16x16x4_f32 v[164:167], v108, v102, 0
	v_add_f32_e32 v161, v106, v161
	v_mul_f32_e64 v169, |v161|, s68
	v_exp_f32_e32 v108, v169
	v_min_f32_e32 v177, 0, v160
	v_add_f32_e32 v160, 1.0, v168
	ds_read2st64_b32 v[168:169], v1 offset0:14 offset1:15
	v_add_f32_e32 v108, 1.0, v108
	v_mfma_f32_16x16x4_f32 v[164:167], v109, v103, v[164:167]
	v_log_f32_e32 v160, v160
	v_log_f32_e32 v108, v108
	v_min_f32_e32 v1, 0, v161
	v_add_f32_e32 v178, v106, v163
	v_fmac_f32_e32 v177, 0xbf317218, v160
	v_fmac_f32_e32 v1, 0xbf317218, v108
	v_add_f32_e32 v108, v106, v162
	s_waitcnt lgkmcnt(0)
	v_mfma_f32_16x16x4_f32 v[160:163], v168, v104, v[164:167]
	v_mul_f32_e64 v109, |v108|, s68
	v_exp_f32_e32 v109, v109
	v_mul_f32_e64 v164, |v178|, s68
	v_exp_f32_e32 v164, v164
	v_min_f32_e32 v108, 0, v108
	v_add_f32_e32 v109, 1.0, v109
	v_log_f32_e32 v109, v109
	v_mfma_f32_16x16x4_f32 v[160:163], v169, v105, v[160:163]
	v_add_f32_e32 v164, 1.0, v164
	v_log_f32_e32 v164, v164
	v_fmac_f32_e32 v108, 0xbf317218, v109
	v_min_f32_e32 v109, 0, v178
	v_fmac_f32_e32 v109, 0xbf317218, v164
	s_nop 4
	v_add_f32_e32 v160, v106, v160
	v_mul_f32_e64 v165, |v160|, s68
	v_exp_f32_e32 v165, v165
	v_add_f32_e32 v161, v106, v161
	v_min_f32_e32 v160, 0, v160
	v_add_f32_e32 v162, v106, v162
	v_add_f32_e32 v164, 1.0, v165
	v_mul_f32_e64 v165, |v161|, s68
	v_log_f32_e32 v164, v164
	v_exp_f32_e32 v165, v165
	v_add_f32_e32 v163, v106, v163
	v_mul_f32_e64 v166, |v163|, s68
	v_fmac_f32_e32 v160, 0xbf317218, v164
	v_add_f32_e32 v164, 1.0, v165
	v_mul_f32_e64 v165, |v162|, s68
	v_log_f32_e32 v164, v164
	v_exp_f32_e32 v165, v165
	v_exp_f32_e32 v166, v166
	v_min_f32_e32 v161, 0, v161
	v_fmac_f32_e32 v161, 0xbf317218, v164
	v_add_f32_e32 v164, 1.0, v165
	v_log_f32_e32 v164, v164
	v_add_f32_e32 v165, 1.0, v166
	v_log_f32_e32 v165, v165
	v_min_f32_e32 v162, 0, v162
	v_fmac_f32_e32 v162, 0xbf317218, v164
	v_min_f32_e32 v163, 0, v163
	v_fma_f32 v164, v170, s31, 0
	v_fmac_f32_e32 v163, 0xbf317218, v165
	v_fmamk_f32 v165, v171, 0x3d800000, v164
	v_fmamk_f32 v166, v172, 0x3d800000, v165
	v_fmamk_f32 v107, v107, 0x3d800000, v166
	v_fmamk_f32 v167, v173, 0x3d800000, v107
	v_fmamk_f32 v168, v175, 0x3d800000, v167
	v_fmamk_f32 v169, v174, 0x3d800000, v168
	v_fmamk_f32 v170, v176, 0x3d800000, v169
	v_fmamk_f32 v171, v177, 0x3d800000, v170
	v_fmamk_f32 v1, v1, 0x3d800000, v171
	v_fmamk_f32 v108, v108, 0x3d800000, v1
	v_fmamk_f32 v109, v109, 0x3d800000, v108
	v_fmamk_f32 v160, v160, 0x3d800000, v109
	v_fmamk_f32 v161, v161, 0x3d800000, v160
	v_fmamk_f32 v162, v162, 0x3d800000, v161
	v_fmamk_f32 v163, v163, 0x3d800000, v162
	ds_bpermute_b32 v172, v137, v163
	ds_bpermute_b32 v173, v138, v163
	ds_bpermute_b32 v174, v139, v163
	s_waitcnt lgkmcnt(2)
	v_cndmask_b32_e64 v172, v172, 0, s[10:11]
	s_waitcnt lgkmcnt(1)
	v_cndmask_b32_e64 v173, 0, v173, s[12:13]
	v_add_f32_e32 v172, v172, v173
	s_waitcnt lgkmcnt(0)
	v_cndmask_b32_e64 v173, 0, v174, s[6:7]
	v_add_f32_e32 v172, v172, v173
	v_add_f32_e32 v164, v164, v172
	v_add_f32_e32 v165, v165, v172
	ds_write2st64_b32 v141, v164, v165 offset0:24 offset1:26
	v_add_f32_e32 v164, v166, v172
	v_add_f32_e32 v107, v107, v172
	ds_write2st64_b32 v141, v164, v107 offset0:28 offset1:30
	v_add_f32_e32 v107, v167, v172
	v_add_f32_e32 v164, v168, v172
	ds_write2st64_b32 v141, v107, v164 offset0:32 offset1:34
	v_add_f32_e32 v107, v169, v172
	v_add_f32_e32 v164, v170, v172
	ds_write2st64_b32 v141, v107, v164 offset0:36 offset1:38
	v_add_f32_e32 v107, v171, v172
	v_add_f32_e32 v1, v1, v172
	ds_write2st64_b32 v141, v107, v1 offset0:40 offset1:42
	v_add_f32_e32 v1, v172, v108
	v_add_f32_e32 v107, v172, v109
	ds_write2st64_b32 v141, v1, v107 offset0:44 offset1:46
	v_add_f32_e32 v1, v172, v160
	v_add_f32_e32 v107, v172, v161
	ds_write2st64_b32 v141, v1, v107 offset0:48 offset1:50
	v_add_f32_e32 v1, v172, v162
	v_add_f32_e32 v107, v172, v163
	ds_write2st64_b32 v141, v1, v107 offset0:52 offset1:54
	s_waitcnt lgkmcnt(0)
	s_barrier
	s_and_saveexec_b64 s[50:51], s[4:5]
	s_cbranch_execz .LBB0_504
	ds_read_b32 v1, v127 offset:38400
	v_lshl_add_u32 v107, s79, 9, v127
	s_waitcnt lgkmcnt(0)
	v_mul_f32_e32 v255, 0x3fb8aa3b, v1
	v_exp_f32_e32 v255, v255
	s_nop 0
	ds_write_b32 v107, v255 offset:4096

.LBB0_580:
	s_add_u32 s0, s50, s38
	s_addc_u32 s1, s51, s39
	s_add_u32 s60, s48, s38
	s_addc_u32 s61, s49, s39
	s_add_u32 s31, s60, s46
	s_addc_u32 s44, s61, 0
	s_add_u32 s62, s31, 0x16e40800
	s_addc_u32 s63, s44, 0
	s_and_b32 s59, s58, 1
	s_cmp_eq_u32 s59, 0
	s_cselect_b64 s[44:45], -1, 0
	s_and_b64 s[64:65], s[44:45], exec
	s_cselect_b32 s31, 0xf0, s54
	v_and_b32_e32 v136, 63, v154
	v_lshl_add_u32 v136, v136, 2, s31
	ds_read2st64_b32 v[72:73], v136 offset1:1
	v_lshl_add_u64 v[74:75], s[0:1], 0, v[102:103]
	ds_read2st64_b32 v[80:81], v136 offset0:4 offset1:5
	global_load_dwordx4 v[92:95], v[74:75], off
	global_load_dwordx4 v[96:99], v[74:75], off offset:1024
	ds_read2st64_b32 v[132:133], v136 offset0:2 offset1:3
	v_lshl_add_u64 v[82:83], s[62:63], 0, v[104:105]
	s_waitcnt lgkmcnt(2)
	v_mfma_f32_16x16x4_f32 v[68:71], v72, v155, 0
	v_add_co_u32_e64 v72, s[0:1], s52, v74
	v_mfma_f32_16x16x4_f32 v[68:71], v73, v164, v[68:71]
	s_nop 0
	v_addc_co_u32_e64 v73, s[0:1], 0, v75, s[0:1]
	global_load_dwordx4 v[84:87], v[72:73], off
	global_load_dwordx4 v[88:91], v[72:73], off offset:1024
	v_add_co_u32_e64 v72, s[0:1], s47, v82
	s_nop 1
	v_addc_co_u32_e64 v73, s[0:1], 0, v83, s[0:1]
	s_waitcnt lgkmcnt(0)
	v_mfma_f32_16x16x4_f32 v[124:127], v132, v165, v[68:71]
	v_add_co_u32_e64 v134, s[0:1], s52, v82
	global_load_dwordx4 v[68:71], v[82:83], off
	s_nop 0
	global_load_dwordx4 v[72:75], v[72:73], off
	v_addc_co_u32_e64 v135, s[0:1], 0, v83, s[0:1]
	v_mfma_f32_16x16x4_f32 v[76:79], v80, v155, 0
	v_add_co_u32_e64 v80, s[0:1], s53, v82
	v_mfma_f32_16x16x4_f32 v[124:127], v133, v166, v[124:127]
	v_mfma_f32_16x16x4_f32 v[128:131], v81, v164, v[76:79]
	v_addc_co_u32_e64 v81, s[0:1], 0, v83, s[0:1]
	s_nop 5
	global_load_dwordx4 v[76:79], v[134:135], off
	s_nop 0
	global_load_dwordx4 v[80:83], v[80:81], off
	ds_read2st64_b32 v[134:135], v136 offset0:6 offset1:7
	v_add_f32_e32 v124, v167, v124
	v_min_f32_e32 v137, 0, v124
	v_mul_f32_e64 v124, |v124|, s55
	v_exp_f32_e32 v124, v124
	v_add_f32_e32 v126, v167, v126
	v_mul_f32_e64 v133, |v126|, s55
	v_exp_f32_e32 v133, v133
	v_add_f32_e32 v124, 1.0, v124
	v_log_f32_e32 v124, v124
	s_waitcnt lgkmcnt(0)
	v_mfma_f32_16x16x4_f32 v[128:131], v134, v165, v[128:131]
	v_add_f32_e32 v133, 1.0, v133
	v_min_f32_e32 v139, 0, v126
	v_fmac_f32_e32 v137, 0xbf317218, v124
	v_log_f32_e32 v124, v133
	v_add_f32_e32 v134, v167, v127
	v_add_f32_e32 v125, v167, v125
	v_mul_f32_e64 v132, |v125|, s55
	v_fmac_f32_e32 v139, 0xbf317218, v124
	v_mul_f32_e64 v124, |v134|, s55
	v_min_f32_e32 v138, 0, v125
	v_exp_f32_e32 v140, v124
	v_mfma_f32_16x16x4_f32 v[124:127], v135, v166, v[128:131]
	v_exp_f32_e32 v132, v132
	v_add_f32_e32 v129, 1.0, v140
	v_log_f32_e32 v129, v129
	v_add_f32_e32 v132, 1.0, v132
	v_log_f32_e32 v132, v132
	v_min_f32_e32 v140, 0, v134
	s_nop 3
	v_add_f32_e32 v124, v167, v124
	v_mul_f32_e64 v128, |v124|, s55
	v_fmac_f32_e32 v138, 0xbf317218, v132
	v_exp_f32_e32 v128, v128
	ds_read2st64_b32 v[132:133], v136 offset0:8 offset1:9
	v_min_f32_e32 v141, 0, v124
	v_fmac_f32_e32 v140, 0xbf317218, v129
	v_add_f32_e32 v128, 1.0, v128
	v_log_f32_e32 v128, v128
	ds_read2st64_b32 v[134:135], v136 offset0:10 offset1:11
	v_add_f32_e32 v124, v167, v125
	v_mul_f32_e64 v125, |v124|, s55
	v_fmac_f32_e32 v141, 0xbf317218, v128
	s_waitcnt lgkmcnt(1)
	v_mfma_f32_16x16x4_f32 v[128:131], v132, v155, 0
	v_add_f32_e32 v132, v167, v126
	v_exp_f32_e32 v125, v125
	v_mul_f32_e64 v126, |v132|, s55
	v_exp_f32_e32 v126, v126
	v_min_f32_e32 v142, 0, v124
	v_add_f32_e32 v124, 1.0, v125
	v_add_f32_e32 v144, v167, v127
	v_mfma_f32_16x16x4_f32 v[128:131], v133, v164, v[128:131]
	v_log_f32_e32 v133, v124
	v_add_f32_e32 v124, 1.0, v126
	v_log_f32_e32 v143, v124
	v_mul_f32_e64 v145, |v144|, s55
	v_fmac_f32_e32 v142, 0xbf317218, v133
	s_waitcnt lgkmcnt(0)
	v_mfma_f32_16x16x4_f32 v[124:127], v134, v165, v[128:131]
	s_nop 2
	v_exp_f32_e32 v128, v145
	v_min_f32_e32 v145, 0, v132
	ds_read2st64_b32 v[132:133], v136 offset0:12 offset1:13
	v_fmac_f32_e32 v145, 0xbf317218, v143
	v_add_f32_e32 v128, 1.0, v128
	v_log_f32_e32 v128, v128
	v_min_f32_e32 v143, 0, v144
	v_mfma_f32_16x16x4_f32 v[124:127], v135, v166, v[124:127]
	v_fmac_f32_e32 v143, 0xbf317218, v128
	s_nop 8
	v_add_f32_e32 v124, v167, v124
	v_mul_f32_e64 v128, |v124|, s55
	v_exp_f32_e32 v134, v128
	s_waitcnt lgkmcnt(0)
	v_mfma_f32_16x16x4_f32 v[128:131], v132, v155, 0
	v_add_f32_e32 v125, v167, v125
	v_mul_f32_e64 v135, |v125|, s55
	v_exp_f32_e32 v132, v135
	v_min_f32_e32 v144, 0, v124
	v_add_f32_e32 v124, 1.0, v134
	ds_read2st64_b32 v[134:135], v136 offset0:14 offset1:15
	v_add_f32_e32 v132, 1.0, v132
	v_mfma_f32_16x16x4_f32 v[128:131], v133, v164, v[128:131]
	v_log_f32_e32 v132, v132
	v_log_f32_e32 v124, v124
	v_min_f32_e32 v133, 0, v125
	v_add_f32_e32 v146, v167, v127
	v_fmac_f32_e32 v133, 0xbf317218, v132
	v_add_f32_e32 v132, v167, v126
	v_fmac_f32_e32 v144, 0xbf317218, v124
	v_mul_f32_e64 v124, |v132|, s55
	v_exp_f32_e32 v136, v124
	s_waitcnt lgkmcnt(0)
	v_mfma_f32_16x16x4_f32 v[124:127], v134, v165, v[128:131]
	v_mul_f32_e64 v128, |v146|, s55
	v_exp_f32_e32 v128, v128
	v_add_f32_e32 v130, 1.0, v136
	v_log_f32_e32 v130, v130
	v_min_f32_e32 v129, 0, v132
	v_add_f32_e32 v128, 1.0, v128
	v_log_f32_e32 v128, v128
	v_mfma_f32_16x16x4_f32 v[124:127], v135, v166, v[124:127]
	v_fmac_f32_e32 v129, 0xbf317218, v130
	v_min_f32_e32 v130, 0, v146
	v_fmac_f32_e32 v130, 0xbf317218, v128
	s_nop 6
	v_add_f32_e32 v124, v167, v124
	v_mul_f32_e64 v131, |v124|, s55
	v_exp_f32_e32 v131, v131
	v_add_f32_e32 v125, v167, v125
	v_min_f32_e32 v124, 0, v124
	v_add_f32_e32 v126, v167, v126
	v_add_f32_e32 v128, 1.0, v131
	v_mul_f32_e64 v131, |v125|, s55
	v_log_f32_e32 v128, v128
	v_exp_f32_e32 v131, v131
	v_add_f32_e32 v127, v167, v127
	v_mul_f32_e64 v132, |v127|, s55
	v_fmac_f32_e32 v124, 0xbf317218, v128
	v_add_f32_e32 v128, 1.0, v131
	v_mul_f32_e64 v131, |v126|, s55
	v_log_f32_e32 v128, v128
	v_exp_f32_e32 v131, v131
	v_exp_f32_e32 v132, v132
	v_min_f32_e32 v125, 0, v125
	v_fmac_f32_e32 v125, 0xbf317218, v128
	v_add_f32_e32 v128, 1.0, v131
	v_add_f32_e32 v131, 1.0, v132
	v_log_f32_e32 v131, v131
	v_log_f32_e32 v128, v128
	v_min_f32_e32 v127, 0, v127
	v_min_f32_e32 v126, 0, v126
	v_fmac_f32_e32 v127, 0xbf317218, v131
	v_fmac_f32_e32 v126, 0xbf317218, v128
	v_fma_f32 v127, v127, s56, 0
	v_fmamk_f32 v126, v126, 0x3d800000, v127
	v_fmamk_f32 v125, v125, 0x3d800000, v126
	v_fmamk_f32 v124, v124, 0x3d800000, v125
	v_fmamk_f32 v128, v130, 0x3d800000, v124
	v_fmamk_f32 v129, v129, 0x3d800000, v128
	v_fmamk_f32 v130, v133, 0x3d800000, v129
	v_fmamk_f32 v131, v144, 0x3d800000, v130
	v_fmamk_f32 v132, v143, 0x3d800000, v131
	v_fmamk_f32 v133, v145, 0x3d800000, v132
	v_fmamk_f32 v134, v142, 0x3d800000, v133
	v_fmamk_f32 v135, v141, 0x3d800000, v134
	v_fmamk_f32 v136, v140, 0x3d800000, v135
	v_fmamk_f32 v139, v139, 0x3d800000, v136
	v_fmamk_f32 v138, v138, 0x3d800000, v139
	v_fmamk_f32 v137, v137, 0x3d800000, v138
	ds_bpermute_b32 v140, v174, v137
	ds_bpermute_b32 v141, v173, v137
	ds_bpermute_b32 v142, v172, v137
	s_waitcnt lgkmcnt(2)
	v_cndmask_b32_e64 v140, v140, 0, s[2:3]
	s_waitcnt lgkmcnt(1)
	v_cndmask_b32_e64 v141, 0, v141, s[4:5]
	v_add_f32_e32 v140, v141, v140
	s_waitcnt lgkmcnt(0)
	v_cndmask_b32_e64 v141, 0, v142, s[6:7]
	v_add_f32_e32 v140, v141, v140
	v_add_f32_e32 v137, v140, v137
	v_add_f32_e32 v138, v140, v138
	v_add_f32_e32 v124, v140, v124
	v_add_f32_e32 v125, v140, v125
	ds_write2st64_b32 v184, v137, v138 offset0:24 offset1:26
	v_add_f32_e32 v137, v140, v139
	v_add_f32_e32 v136, v140, v136
	v_add_f32_e32 v135, v140, v135
	v_add_f32_e32 v134, v140, v134
	v_add_f32_e32 v133, v140, v133
	v_add_f32_e32 v132, v140, v132
	v_add_f32_e32 v131, v140, v131
	v_add_f32_e32 v130, v140, v130
	v_add_f32_e32 v129, v140, v129
	v_add_f32_e32 v128, v140, v128
	ds_write2st64_b32 v184, v124, v125 offset0:48 offset1:50
	v_add_f32_e32 v124, v140, v126
	v_add_f32_e32 v125, v140, v127
	ds_write2st64_b32 v184, v137, v136 offset0:28 offset1:30
	ds_write2st64_b32 v184, v135, v134 offset0:32 offset1:34
	ds_write2st64_b32 v184, v133, v132 offset0:36 offset1:38
	ds_write2st64_b32 v184, v131, v130 offset0:40 offset1:42
	ds_write2st64_b32 v184, v129, v128 offset0:44 offset1:46
	ds_write2st64_b32 v184, v124, v125 offset0:52 offset1:54
	s_waitcnt lgkmcnt(0)
	s_barrier
	s_and_saveexec_b64 s[0:1], s[8:9]
	s_cbranch_execz .LBB0_582
	ds_read_b32 v124, v175 offset:6144
	v_lshl_add_u32 v125, s59, 9, v175
	s_waitcnt lgkmcnt(0)
	v_mul_f32_e32 v255, 0x3fb8aa3b, v124
	v_exp_f32_e32 v255, v255
	s_nop 0
	ds_write_b32 v125, v255 offset:4096

.LBB0_664:
	s_add_u32 s62, s61, s76
	s_addc_u32 s63, s91, s77
	v_lshl_add_u64 v[70:71], s[62:63], 0, v[112:113]
	s_add_u32 s62, s55, s76
	s_addc_u32 s63, s57, s77
	s_add_u32 s62, s62, s68
	v_add_co_u32_e32 v74, vcc, s95, v70
	s_addc_u32 s63, s63, 0
	s_nop 0
	v_addc_co_u32_e32 v75, vcc, 0, v71, vcc
	v_lshl_add_u64 v[86:87], s[62:63], 0, v[114:115]
	v_add_co_u32_e32 v78, vcc, s81, v86
	s_and_b32 s93, s92, 1
	s_add_i32 s69, s66, 0xf0
	v_addc_co_u32_e32 v79, vcc, 0, v87, vcc
	s_cmp_eq_u32 s93, 0
	v_add_co_u32_e32 v82, vcc, s95, v86
	s_cselect_b64 s[78:79], -1, 0
	s_nop 0
	v_addc_co_u32_e32 v83, vcc, 0, v87, vcc
	s_and_b64 s[62:63], s[78:79], exec
	global_load_dwordx4 v[94:97], v[70:71], off
	global_load_dwordx4 v[98:101], v[70:71], off offset:1024
	s_nop 0
	global_load_dwordx4 v[70:73], v[74:75], off
	global_load_dwordx4 v[90:93], v[74:75], off offset:1024
	s_cselect_b32 s62, 0xf0, s69
	global_load_dwordx4 v[74:77], v[86:87], off
	v_add_co_u32_e32 v86, vcc, s96, v86
	v_and_b32_e32 v137, 63, v154
	v_lshl_add_u32 v137, v137, 2, s62
	s_nop 0
	v_addc_co_u32_e32 v87, vcc, 0, v87, vcc
	global_load_dwordx4 v[78:81], v[78:79], off
	s_nop 0
	global_load_dwordx4 v[82:85], v[82:83], off
	s_nop 0
	global_load_dwordx4 v[86:89], v[86:87], off
	ds_read2st64_b32 v[134:135], v137 offset1:1
	ds_read2st64_b32 v[142:143], v137 offset0:2 offset1:3
	s_waitcnt lgkmcnt(1)
	v_mfma_f32_16x16x4_f32 v[138:141], v134, v104, 0
	ds_read2st64_b32 v[146:147], v137 offset0:8 offset1:9
	v_mfma_f32_16x16x4_f32 v[138:141], v135, v105, v[138:141]
	s_waitcnt lgkmcnt(1)
	v_mfma_f32_16x16x4_f32 v[138:141], v142, v106, v[138:141]
	v_mfma_f32_16x16x4_f32 v[138:141], v143, v107, v[138:141]
	ds_read2st64_b32 v[142:143], v137 offset0:4 offset1:5
	s_nop 8
	v_add_f32_e32 v134, v108, v138
	v_min_f32_e32 v109, 0, v134
	v_mul_f32_e64 v134, |v134|, s97
	v_exp_f32_e32 v134, v134
	v_add_f32_e32 v135, v108, v139
	v_add_f32_e32 v136, v108, v140
	v_add_f32_e32 v138, v108, v141
	v_add_f32_e32 v134, 1.0, v134
	v_log_f32_e32 v134, v134
	s_nop 0
	v_fmac_f32_e32 v109, 0xbf317218, v134
	v_min_f32_e32 v134, 0, v135
	v_mul_f32_e64 v135, |v135|, s97
	v_exp_f32_e32 v135, v135
	v_fma_f32 v109, v109, s0, 0
	v_add_f32_e32 v135, 1.0, v135
	v_log_f32_e32 v135, v135
	s_nop 0
	v_fmac_f32_e32 v134, 0xbf317218, v135
	v_min_f32_e32 v135, 0, v136
	v_mul_f32_e64 v136, |v136|, s97
	v_exp_f32_e32 v136, v136
	v_fmamk_f32 v134, v134, 0x3d800000, v109
	v_add_f32_e32 v136, 1.0, v136
	v_log_f32_e32 v136, v136
	s_nop 0
	v_fmac_f32_e32 v135, 0xbf317218, v136
	v_min_f32_e32 v136, 0, v138
	v_mul_f32_e64 v138, |v138|, s97
	v_exp_f32_e32 v138, v138
	v_fmamk_f32 v135, v135, 0x3d800000, v134
	v_add_f32_e32 v138, 1.0, v138
	v_log_f32_e32 v138, v138
	s_nop 0
	v_fmac_f32_e32 v136, 0xbf317218, v138
	s_waitcnt lgkmcnt(0)
	v_mfma_f32_16x16x4_f32 v[138:141], v142, v104, 0
	v_fmamk_f32 v136, v136, 0x3d800000, v135
	v_mfma_f32_16x16x4_f32 v[138:141], v143, v105, v[138:141]
	ds_read2st64_b32 v[142:143], v137 offset0:6 offset1:7
	s_waitcnt lgkmcnt(0)
	v_mfma_f32_16x16x4_f32 v[138:141], v142, v106, v[138:141]
	v_mfma_f32_16x16x4_f32 v[138:141], v143, v107, v[138:141]
	s_nop 9
	v_add_f32_e32 v142, v108, v138
	v_min_f32_e32 v138, 0, v142
	v_mul_f32_e64 v142, |v142|, s97
	v_exp_f32_e32 v142, v142
	s_nop 0
	v_add_f32_e32 v142, 1.0, v142
	v_log_f32_e32 v142, v142
	s_nop 0
	v_fmac_f32_e32 v138, 0xbf317218, v142
	v_add_f32_e32 v142, v108, v139
	v_min_f32_e32 v139, 0, v142
	v_mul_f32_e64 v142, |v142|, s97
	v_exp_f32_e32 v142, v142
	s_nop 0
	v_add_f32_e32 v142, 1.0, v142
	v_log_f32_e32 v142, v142
	s_nop 0
	v_fmac_f32_e32 v139, 0xbf317218, v142
	v_add_f32_e32 v142, v108, v140
	v_min_f32_e32 v140, 0, v142
	v_mul_f32_e64 v142, |v142|, s97
	v_exp_f32_e32 v142, v142
	s_nop 0
	v_add_f32_e32 v142, 1.0, v142
	v_log_f32_e32 v142, v142
	s_nop 0
	v_fmac_f32_e32 v140, 0xbf317218, v142
	v_add_f32_e32 v142, v108, v141
	v_min_f32_e32 v141, 0, v142
	v_mul_f32_e64 v142, |v142|, s97
	v_exp_f32_e32 v142, v142
	s_nop 0
	v_add_f32_e32 v142, 1.0, v142
	v_log_f32_e32 v142, v142
	s_nop 0
	v_fmac_f32_e32 v141, 0xbf317218, v142
	v_mfma_f32_16x16x4_f32 v[142:145], v146, v104, 0
	v_mfma_f32_16x16x4_f32 v[142:145], v147, v105, v[142:145]
	ds_read2st64_b32 v[146:147], v137 offset0:10 offset1:11
	s_waitcnt lgkmcnt(0)
	v_mfma_f32_16x16x4_f32 v[142:145], v146, v106, v[142:145]
	v_mfma_f32_16x16x4_f32 v[142:145], v147, v107, v[142:145]
	ds_read2st64_b32 v[146:147], v137 offset0:12 offset1:13
	s_nop 8
	v_add_f32_e32 v142, v108, v142
	v_min_f32_e32 v148, 0, v142
	v_mul_f32_e64 v142, |v142|, s97
	v_exp_f32_e32 v142, v142
	s_nop 0
	v_add_f32_e32 v142, 1.0, v142
	v_log_f32_e32 v142, v142
	s_nop 0
	v_fmac_f32_e32 v148, 0xbf317218, v142
	v_add_f32_e32 v142, v108, v143
	v_min_f32_e32 v149, 0, v142
	v_mul_f32_e64 v142, |v142|, s97
	v_exp_f32_e32 v142, v142
	s_nop 0
	v_add_f32_e32 v142, 1.0, v142
	v_log_f32_e32 v142, v142
	s_nop 0
	v_fmac_f32_e32 v149, 0xbf317218, v142
	v_add_f32_e32 v142, v108, v144
	v_min_f32_e32 v150, 0, v142
	v_mul_f32_e64 v142, |v142|, s97
	v_exp_f32_e32 v142, v142
	s_nop 0
	v_add_f32_e32 v142, 1.0, v142
	v_log_f32_e32 v142, v142
	s_nop 0
	v_fmac_f32_e32 v150, 0xbf317218, v142
	v_add_f32_e32 v142, v108, v145
	v_min_f32_e32 v151, 0, v142
	v_mul_f32_e64 v142, |v142|, s97
	v_exp_f32_e32 v142, v142
	s_nop 0
	v_add_f32_e32 v142, 1.0, v142
	v_log_f32_e32 v142, v142
	s_nop 0
	v_fmac_f32_e32 v151, 0xbf317218, v142
	s_waitcnt lgkmcnt(0)
	v_mfma_f32_16x16x4_f32 v[142:145], v146, v104, 0
	v_mfma_f32_16x16x4_f32 v[142:145], v147, v105, v[142:145]
	ds_read2st64_b32 v[146:147], v137 offset0:14 offset1:15
	s_waitcnt lgkmcnt(0)
	v_mfma_f32_16x16x4_f32 v[142:145], v146, v106, v[142:145]
	v_mfma_f32_16x16x4_f32 v[142:145], v147, v107, v[142:145]
	s_nop 9
	v_add_f32_e32 v137, v108, v142
	v_min_f32_e32 v142, 0, v137
	v_mul_f32_e64 v137, |v137|, s97
	v_exp_f32_e32 v137, v137
	s_nop 0
	v_add_f32_e32 v137, 1.0, v137
	v_log_f32_e32 v137, v137
	s_nop 0
	v_fmac_f32_e32 v142, 0xbf317218, v137
	v_add_f32_e32 v137, v108, v143
	v_min_f32_e32 v143, 0, v137
	v_mul_f32_e64 v137, |v137|, s97
	v_exp_f32_e32 v137, v137
	s_nop 0
	v_add_f32_e32 v137, 1.0, v137
	v_log_f32_e32 v137, v137
	s_nop 0
	v_fmac_f32_e32 v143, 0xbf317218, v137
	v_add_f32_e32 v137, v108, v144
	v_min_f32_e32 v144, 0, v137
	v_mul_f32_e64 v137, |v137|, s97
	v_exp_f32_e32 v137, v137
	s_nop 0
	v_add_f32_e32 v137, 1.0, v137
	v_log_f32_e32 v137, v137
	s_nop 0
	v_fmac_f32_e32 v144, 0xbf317218, v137
	v_add_f32_e32 v137, v108, v145
	v_min_f32_e32 v145, 0, v137
	v_mul_f32_e64 v137, |v137|, s97
	v_exp_f32_e32 v137, v137
	s_nop 0
	v_add_f32_e32 v137, 1.0, v137
	v_log_f32_e32 v137, v137
	s_nop 0
	v_fmac_f32_e32 v145, 0xbf317218, v137
	v_fmamk_f32 v137, v138, 0x3d800000, v136
	v_fmamk_f32 v138, v139, 0x3d800000, v137
	v_fmamk_f32 v139, v140, 0x3d800000, v138
	v_fmamk_f32 v140, v141, 0x3d800000, v139
	v_fmamk_f32 v141, v148, 0x3d800000, v140
	v_fmamk_f32 v146, v149, 0x3d800000, v141
	v_fmamk_f32 v147, v150, 0x3d800000, v146
	v_fmamk_f32 v148, v151, 0x3d800000, v147
	v_fmamk_f32 v142, v142, 0x3d800000, v148
	v_fmamk_f32 v143, v143, 0x3d800000, v142
	v_fmamk_f32 v144, v144, 0x3d800000, v143
	v_fmamk_f32 v145, v145, 0x3d800000, v144
	ds_bpermute_b32 v149, v186, v145
	ds_bpermute_b32 v150, v187, v145
	ds_bpermute_b32 v151, v188, v145
	s_waitcnt lgkmcnt(2)
	v_cndmask_b32_e64 v149, v149, 0, s[4:5]
	s_waitcnt lgkmcnt(1)
	v_cndmask_b32_e64 v150, 0, v150, s[6:7]
	v_add_f32_e32 v149, v149, v150
	s_waitcnt lgkmcnt(0)
	v_cndmask_b32_e64 v150, 0, v151, s[8:9]
	v_add_f32_e32 v149, v149, v150
	v_add_f32_e32 v109, v109, v149
	v_add_f32_e32 v134, v134, v149
	ds_write2st64_b32 v200, v109, v134 offset0:24 offset1:26
	v_add_f32_e32 v109, v135, v149
	v_add_f32_e32 v134, v136, v149
	ds_write2st64_b32 v200, v109, v134 offset0:28 offset1:30
	v_add_f32_e32 v109, v137, v149
	v_add_f32_e32 v134, v138, v149
	ds_write2st64_b32 v200, v109, v134 offset0:32 offset1:34
	v_add_f32_e32 v109, v139, v149
	v_add_f32_e32 v134, v140, v149
	ds_write2st64_b32 v200, v109, v134 offset0:36 offset1:38
	v_add_f32_e32 v109, v141, v149
	v_add_f32_e32 v134, v146, v149
	ds_write2st64_b32 v200, v109, v134 offset0:40 offset1:42
	v_add_f32_e32 v109, v149, v147
	v_add_f32_e32 v134, v149, v148
	ds_write2st64_b32 v200, v109, v134 offset0:44 offset1:46
	v_add_f32_e32 v109, v149, v142
	v_add_f32_e32 v134, v149, v143
	ds_write2st64_b32 v200, v109, v134 offset0:48 offset1:50
	v_add_f32_e32 v109, v149, v144
	v_add_f32_e32 v134, v149, v145
	ds_write2st64_b32 v200, v109, v134 offset0:52 offset1:54
	s_waitcnt lgkmcnt(0)
	s_barrier
	s_and_saveexec_b64 s[62:63], s[10:11]
	s_cbranch_execz .LBB0_666
	ds_read_b32 v109, v178 offset:38400
	v_lshl_add_u32 v134, s93, 9, v178
	s_waitcnt lgkmcnt(0)
	v_mul_f32_e32 v255, 0x3fb8aa3b, v109
	v_exp_f32_e32 v255, v255
	s_nop 0
	ds_write_b32 v134, v255 offset:4096

.LBB0_680:
	s_add_u32 s62, s71, s60
	s_addc_u32 s63, s74, s61
	s_add_u32 s72, s48, s60
	s_addc_u32 s73, s70, s61
	s_add_u32 s55, s72, s68
	v_lshl_add_u64 v[70:71], s[62:63], 0, v[112:113]
	s_addc_u32 s63, s73, 0
	s_add_u32 s62, s55, 0xafc0800
	v_add_co_u32_e32 v74, vcc, s95, v70
	s_addc_u32 s63, s63, 0
	s_nop 0
	v_addc_co_u32_e32 v75, vcc, 0, v71, vcc
	v_lshl_add_u64 v[86:87], s[62:63], 0, v[114:115]
	v_add_co_u32_e32 v78, vcc, s81, v86
	s_and_b32 s67, s75, 1
	s_nop 0
	v_addc_co_u32_e32 v79, vcc, 0, v87, vcc
	s_cmp_eq_u32 s67, 0
	v_add_co_u32_e32 v82, vcc, s95, v86
	s_cselect_b64 s[64:65], -1, 0
	s_nop 0
	v_addc_co_u32_e32 v83, vcc, 0, v87, vcc
	s_and_b64 s[62:63], s[64:65], exec
	global_load_dwordx4 v[94:97], v[70:71], off
	global_load_dwordx4 v[98:101], v[70:71], off offset:1024
	s_nop 0
	global_load_dwordx4 v[70:73], v[74:75], off
	global_load_dwordx4 v[90:93], v[74:75], off offset:1024
	s_cselect_b32 s55, 0xf0, s69
	global_load_dwordx4 v[74:77], v[86:87], off
	v_add_co_u32_e32 v86, vcc, s96, v86
	v_and_b32_e32 v105, 63, v154
	v_lshl_add_u32 v105, v105, 2, s55
	s_nop 0
	v_addc_co_u32_e32 v87, vcc, 0, v87, vcc
	global_load_dwordx4 v[78:81], v[78:79], off
	s_nop 0
	global_load_dwordx4 v[82:85], v[82:83], off
	s_nop 0
	global_load_dwordx4 v[86:89], v[86:87], off
	ds_read2st64_b32 v[102:103], v105 offset1:1
	ds_read2st64_b32 v[136:137], v105 offset0:2 offset1:3
	s_waitcnt vmcnt(12) lgkmcnt(1)
	v_mfma_f32_16x16x4_f32 v[106:109], v102, v219, 0
	ds_read2st64_b32 v[140:141], v105 offset0:8 offset1:9
	s_waitcnt vmcnt(11)
	v_mfma_f32_16x16x4_f32 v[106:109], v103, v220, v[106:109]
	s_waitcnt vmcnt(10) lgkmcnt(1)
	v_mfma_f32_16x16x4_f32 v[106:109], v136, v221, v[106:109]
	s_waitcnt vmcnt(9)
	v_mfma_f32_16x16x4_f32 v[106:109], v137, v222, v[106:109]
	ds_read2st64_b32 v[136:137], v105 offset0:4 offset1:5
	s_waitcnt vmcnt(8)
	s_nop 7
	v_add_f32_e32 v102, v223, v106
	v_min_f32_e32 v0, 0, v102
	v_mul_f32_e64 v102, |v102|, s97
	v_exp_f32_e32 v102, v102
	v_add_f32_e32 v103, v223, v107
	v_add_f32_e32 v104, v223, v108
	v_add_f32_e32 v106, v223, v109
	v_add_f32_e32 v102, 1.0, v102
	v_log_f32_e32 v102, v102
	s_nop 0
	v_fmac_f32_e32 v0, 0xbf317218, v102
	v_min_f32_e32 v102, 0, v103
	v_mul_f32_e64 v103, |v103|, s97
	v_exp_f32_e32 v103, v103
	s_nop 0
	v_add_f32_e32 v103, 1.0, v103
	v_log_f32_e32 v103, v103
	s_nop 0
	v_fmac_f32_e32 v102, 0xbf317218, v103
	v_min_f32_e32 v103, 0, v104
	v_mul_f32_e64 v104, |v104|, s97
	v_exp_f32_e32 v104, v104
	s_nop 0
	v_add_f32_e32 v104, 1.0, v104
	v_log_f32_e32 v104, v104
	s_nop 0
	v_fmac_f32_e32 v103, 0xbf317218, v104
	v_min_f32_e32 v104, 0, v106
	v_mul_f32_e64 v106, |v106|, s97
	v_exp_f32_e32 v106, v106
	s_nop 0
	v_add_f32_e32 v106, 1.0, v106
	v_log_f32_e32 v106, v106
	s_nop 0
	v_fmac_f32_e32 v104, 0xbf317218, v106
	s_waitcnt lgkmcnt(0)
	v_mfma_f32_16x16x4_f32 v[106:109], v136, v219, 0
	v_mfma_f32_16x16x4_f32 v[106:109], v137, v220, v[106:109]
	ds_read2st64_b32 v[136:137], v105 offset0:6 offset1:7
	s_waitcnt lgkmcnt(0)
	v_mfma_f32_16x16x4_f32 v[106:109], v136, v221, v[106:109]
	v_mfma_f32_16x16x4_f32 v[106:109], v137, v222, v[106:109]
	s_nop 9
	v_add_f32_e32 v136, v223, v106
	v_min_f32_e32 v106, 0, v136
	v_mul_f32_e64 v136, |v136|, s97
	v_exp_f32_e32 v136, v136
	s_nop 0
	v_add_f32_e32 v136, 1.0, v136
	v_log_f32_e32 v136, v136
	s_nop 0
	v_fmac_f32_e32 v106, 0xbf317218, v136
	v_add_f32_e32 v136, v223, v107
	v_min_f32_e32 v107, 0, v136
	v_mul_f32_e64 v136, |v136|, s97
	v_exp_f32_e32 v136, v136
	s_nop 0
	v_add_f32_e32 v136, 1.0, v136
	v_log_f32_e32 v136, v136
	s_nop 0
	v_fmac_f32_e32 v107, 0xbf317218, v136
	v_add_f32_e32 v136, v223, v108
	v_min_f32_e32 v108, 0, v136
	v_mul_f32_e64 v136, |v136|, s97
	v_exp_f32_e32 v136, v136
	s_nop 0
	v_add_f32_e32 v136, 1.0, v136
	v_log_f32_e32 v136, v136
	s_nop 0
	v_fmac_f32_e32 v108, 0xbf317218, v136
	v_add_f32_e32 v136, v223, v109
	v_min_f32_e32 v109, 0, v136
	v_mul_f32_e64 v136, |v136|, s97
	v_exp_f32_e32 v136, v136
	s_nop 0
	v_add_f32_e32 v136, 1.0, v136
	v_log_f32_e32 v136, v136
	s_nop 0
	v_fmac_f32_e32 v109, 0xbf317218, v136
	v_mfma_f32_16x16x4_f32 v[136:139], v140, v219, 0
	v_mfma_f32_16x16x4_f32 v[136:139], v141, v220, v[136:139]
	ds_read2st64_b32 v[140:141], v105 offset0:10 offset1:11
	s_waitcnt lgkmcnt(0)
	v_mfma_f32_16x16x4_f32 v[136:139], v140, v221, v[136:139]
	v_mfma_f32_16x16x4_f32 v[136:139], v141, v222, v[136:139]
	ds_read2st64_b32 v[140:141], v105 offset0:12 offset1:13
	s_nop 8
	v_add_f32_e32 v136, v223, v136
	v_min_f32_e32 v142, 0, v136
	v_mul_f32_e64 v136, |v136|, s97
	v_exp_f32_e32 v136, v136
	s_nop 0
	v_add_f32_e32 v136, 1.0, v136
	v_log_f32_e32 v136, v136
	s_nop 0
	v_fmac_f32_e32 v142, 0xbf317218, v136
	v_add_f32_e32 v136, v223, v137
	v_min_f32_e32 v143, 0, v136
	v_mul_f32_e64 v136, |v136|, s97
	v_exp_f32_e32 v136, v136
	s_nop 0
	v_add_f32_e32 v136, 1.0, v136
	v_log_f32_e32 v136, v136
	s_nop 0
	v_fmac_f32_e32 v143, 0xbf317218, v136
	v_add_f32_e32 v136, v223, v138
	v_min_f32_e32 v144, 0, v136
	v_mul_f32_e64 v136, |v136|, s97
	v_exp_f32_e32 v136, v136
	s_nop 0
	v_add_f32_e32 v136, 1.0, v136
	v_log_f32_e32 v136, v136
	s_nop 0
	v_fmac_f32_e32 v144, 0xbf317218, v136
	v_add_f32_e32 v136, v223, v139
	v_min_f32_e32 v145, 0, v136
	v_mul_f32_e64 v136, |v136|, s97
	v_exp_f32_e32 v136, v136
	s_nop 0
	v_add_f32_e32 v136, 1.0, v136
	v_log_f32_e32 v136, v136
	s_nop 0
	v_fmac_f32_e32 v145, 0xbf317218, v136
	s_waitcnt lgkmcnt(0)
	v_mfma_f32_16x16x4_f32 v[136:139], v140, v219, 0
	v_mfma_f32_16x16x4_f32 v[136:139], v141, v220, v[136:139]
	ds_read2st64_b32 v[140:141], v105 offset0:14 offset1:15
	s_waitcnt lgkmcnt(0)
	v_mfma_f32_16x16x4_f32 v[136:139], v140, v221, v[136:139]
	v_mfma_f32_16x16x4_f32 v[136:139], v141, v222, v[136:139]
	s_nop 9
	v_add_f32_e32 v105, v223, v136
	v_min_f32_e32 v136, 0, v105
	v_mul_f32_e64 v105, |v105|, s97
	v_exp_f32_e32 v105, v105
	s_nop 0
	v_add_f32_e32 v105, 1.0, v105
	v_log_f32_e32 v105, v105
	s_nop 0
	v_fmac_f32_e32 v136, 0xbf317218, v105
	v_add_f32_e32 v105, v223, v137
	v_min_f32_e32 v137, 0, v105
	v_mul_f32_e64 v105, |v105|, s97
	v_exp_f32_e32 v105, v105
	s_nop 0
	v_add_f32_e32 v105, 1.0, v105
	v_log_f32_e32 v105, v105
	s_nop 0
	v_fmac_f32_e32 v137, 0xbf317218, v105
	v_add_f32_e32 v105, v223, v138
	v_min_f32_e32 v138, 0, v105
	v_mul_f32_e64 v105, |v105|, s97
	v_exp_f32_e32 v105, v105
	s_nop 0
	v_add_f32_e32 v105, 1.0, v105
	v_log_f32_e32 v105, v105
	s_nop 0
	v_fmac_f32_e32 v138, 0xbf317218, v105
	v_add_f32_e32 v105, v223, v139
	v_min_f32_e32 v139, 0, v105
	v_mul_f32_e64 v105, |v105|, s97
	v_exp_f32_e32 v105, v105
	s_nop 0
	v_add_f32_e32 v105, 1.0, v105
	v_log_f32_e32 v105, v105
	s_nop 0
	v_fmac_f32_e32 v139, 0xbf317218, v105
	v_fma_f32 v105, v139, s0, 0
	v_fmamk_f32 v138, v138, 0x3d800000, v105
	v_fmamk_f32 v137, v137, 0x3d800000, v138
	v_fmamk_f32 v136, v136, 0x3d800000, v137
	v_fmamk_f32 v139, v145, 0x3d800000, v136
	v_fmamk_f32 v140, v144, 0x3d800000, v139
	v_fmamk_f32 v141, v143, 0x3d800000, v140
	v_fmamk_f32 v142, v142, 0x3d800000, v141
	v_fmamk_f32 v109, v109, 0x3d800000, v142
	v_fmamk_f32 v108, v108, 0x3d800000, v109
	v_fmamk_f32 v107, v107, 0x3d800000, v108
	v_fmamk_f32 v106, v106, 0x3d800000, v107
	v_fmamk_f32 v104, v104, 0x3d800000, v106
	v_fmamk_f32 v103, v103, 0x3d800000, v104
	v_fmamk_f32 v102, v102, 0x3d800000, v103
	v_fmamk_f32 v0, v0, 0x3d800000, v102
	ds_bpermute_b32 v144, v188, v0
	ds_bpermute_b32 v145, v189, v0
	ds_bpermute_b32 v143, v187, v0
	s_waitcnt lgkmcnt(2)
	v_cndmask_b32_e64 v144, 0, v144, s[28:29]
	s_waitcnt lgkmcnt(1)
	v_cndmask_b32_e64 v145, v145, 0, s[8:9]
	v_add_f32_e32 v144, v144, v145
	s_waitcnt lgkmcnt(0)
	v_cndmask_b32_e64 v143, 0, v143, s[4:5]
	v_add_f32_e32 v143, v143, v144
	v_add_f32_e32 v0, v143, v0
	v_add_f32_e32 v102, v143, v102
	ds_write2st64_b32 v200, v0, v102 offset0:24 offset1:26
	v_add_f32_e32 v0, v143, v103
	v_add_f32_e32 v102, v143, v104
	ds_write2st64_b32 v200, v0, v102 offset0:28 offset1:30
	v_add_f32_e32 v0, v143, v106
	v_add_f32_e32 v102, v143, v107
	ds_write2st64_b32 v200, v0, v102 offset0:32 offset1:34
	v_add_f32_e32 v0, v143, v108
	v_add_f32_e32 v102, v143, v109
	ds_write2st64_b32 v200, v0, v102 offset0:36 offset1:38
	v_add_f32_e32 v0, v143, v142
	v_add_f32_e32 v102, v143, v141
	ds_write2st64_b32 v200, v0, v102 offset0:40 offset1:42
	v_add_f32_e32 v0, v143, v140
	v_add_f32_e32 v102, v143, v139
	ds_write2st64_b32 v200, v0, v102 offset0:44 offset1:46
	v_add_f32_e32 v0, v143, v136
	v_add_f32_e32 v102, v143, v137
	ds_write2st64_b32 v200, v0, v102 offset0:48 offset1:50
	v_add_f32_e32 v0, v143, v138
	v_add_f32_e32 v102, v143, v105
	ds_write2st64_b32 v200, v0, v102 offset0:52 offset1:54
	s_waitcnt lgkmcnt(0)
	s_barrier
	s_and_saveexec_b64 s[62:63], s[10:11]
	s_cbranch_execz .LBB0_682
	ds_read_b32 v0, v178 offset:6144
	v_lshl_add_u32 v102, s67, 9, v178
	s_waitcnt lgkmcnt(0)
	v_mul_f32_e32 v255, 0x3fb8aa3b, v0
	v_exp_f32_e32 v255, v255
	s_nop 0
	ds_write_b32 v102, v255 offset:4096

.LBB0_2183:
	s_add_u32 s0, s48, s34
	s_addc_u32 s1, s49, s35
	s_add_u32 s58, s39, s34
	s_addc_u32 s59, s37, s35
	s_add_u32 s42, s58, s44
	s_addc_u32 s43, s59, 0
	s_add_u32 s60, s42, 0x16e40800
	s_addc_u32 s61, s43, 0
	s_and_b32 s57, s56, 1
	s_cmp_eq_u32 s57, 0
	s_cselect_b64 s[42:43], -1, 0
	s_and_b64 s[62:63], s[42:43], exec
	s_cselect_b32 s62, 0xf0, s52
	v_and_b32_e32 v136, 63, v154
	v_lshl_add_u32 v136, v136, 2, s62
	ds_read2st64_b32 v[72:73], v136 offset1:1
	v_lshl_add_u64 v[74:75], s[0:1], 0, v[102:103]
	ds_read2st64_b32 v[80:81], v136 offset0:4 offset1:5
	global_load_dwordx4 v[92:95], v[74:75], off
	global_load_dwordx4 v[96:99], v[74:75], off offset:1024
	ds_read2st64_b32 v[132:133], v136 offset0:2 offset1:3
	v_lshl_add_u64 v[82:83], s[60:61], 0, v[104:105]
	s_waitcnt lgkmcnt(2)
	v_mfma_f32_16x16x4_f32 v[68:71], v72, v155, 0
	v_add_co_u32_e64 v72, s[0:1], s50, v74
	v_mfma_f32_16x16x4_f32 v[68:71], v73, v164, v[68:71]
	s_nop 0
	v_addc_co_u32_e64 v73, s[0:1], 0, v75, s[0:1]
	global_load_dwordx4 v[84:87], v[72:73], off
	global_load_dwordx4 v[88:91], v[72:73], off offset:1024
	v_add_co_u32_e64 v72, s[0:1], s45, v82
	s_nop 1
	v_addc_co_u32_e64 v73, s[0:1], 0, v83, s[0:1]
	s_waitcnt lgkmcnt(0)
	v_mfma_f32_16x16x4_f32 v[124:127], v132, v165, v[68:71]
	v_add_co_u32_e64 v134, s[0:1], s50, v82
	global_load_dwordx4 v[68:71], v[82:83], off
	s_nop 0
	global_load_dwordx4 v[72:75], v[72:73], off
	v_addc_co_u32_e64 v135, s[0:1], 0, v83, s[0:1]
	v_mfma_f32_16x16x4_f32 v[76:79], v80, v155, 0
	v_add_co_u32_e64 v80, s[0:1], s51, v82
	v_mfma_f32_16x16x4_f32 v[124:127], v133, v166, v[124:127]
	v_mfma_f32_16x16x4_f32 v[128:131], v81, v164, v[76:79]
	v_addc_co_u32_e64 v81, s[0:1], 0, v83, s[0:1]
	s_nop 5
	global_load_dwordx4 v[76:79], v[134:135], off
	s_nop 0
	global_load_dwordx4 v[80:83], v[80:81], off
	ds_read2st64_b32 v[134:135], v136 offset0:6 offset1:7
	v_add_f32_e32 v124, v167, v124
	v_min_f32_e32 v137, 0, v124
	v_mul_f32_e64 v124, |v124|, s53
	v_exp_f32_e32 v124, v124
	v_add_f32_e32 v126, v167, v126
	v_mul_f32_e64 v133, |v126|, s53
	v_exp_f32_e32 v133, v133
	v_add_f32_e32 v124, 1.0, v124
	v_log_f32_e32 v124, v124
	s_waitcnt lgkmcnt(0)
	v_mfma_f32_16x16x4_f32 v[128:131], v134, v165, v[128:131]
	v_add_f32_e32 v133, 1.0, v133
	v_min_f32_e32 v139, 0, v126
	v_fmac_f32_e32 v137, 0xbf317218, v124
	v_log_f32_e32 v124, v133
	v_add_f32_e32 v134, v167, v127
	v_add_f32_e32 v125, v167, v125
	v_mul_f32_e64 v132, |v125|, s53
	v_fmac_f32_e32 v139, 0xbf317218, v124
	v_mul_f32_e64 v124, |v134|, s53
	v_min_f32_e32 v138, 0, v125
	v_exp_f32_e32 v140, v124
	v_mfma_f32_16x16x4_f32 v[124:127], v135, v166, v[128:131]
	v_exp_f32_e32 v132, v132
	v_add_f32_e32 v129, 1.0, v140
	v_log_f32_e32 v129, v129
	v_add_f32_e32 v132, 1.0, v132
	v_log_f32_e32 v132, v132
	v_min_f32_e32 v140, 0, v134
	s_nop 3
	v_add_f32_e32 v124, v167, v124
	v_mul_f32_e64 v128, |v124|, s53
	v_fmac_f32_e32 v138, 0xbf317218, v132
	v_exp_f32_e32 v128, v128
	ds_read2st64_b32 v[132:133], v136 offset0:8 offset1:9
	v_min_f32_e32 v141, 0, v124
	v_fmac_f32_e32 v140, 0xbf317218, v129
	v_add_f32_e32 v128, 1.0, v128
	v_log_f32_e32 v128, v128
	ds_read2st64_b32 v[134:135], v136 offset0:10 offset1:11
	v_add_f32_e32 v124, v167, v125
	v_mul_f32_e64 v125, |v124|, s53
	v_fmac_f32_e32 v141, 0xbf317218, v128
	s_waitcnt lgkmcnt(1)
	v_mfma_f32_16x16x4_f32 v[128:131], v132, v155, 0
	v_add_f32_e32 v132, v167, v126
	v_exp_f32_e32 v125, v125
	v_mul_f32_e64 v126, |v132|, s53
	v_exp_f32_e32 v126, v126
	v_min_f32_e32 v142, 0, v124
	v_add_f32_e32 v124, 1.0, v125
	v_add_f32_e32 v144, v167, v127
	v_mfma_f32_16x16x4_f32 v[128:131], v133, v164, v[128:131]
	v_log_f32_e32 v133, v124
	v_add_f32_e32 v124, 1.0, v126
	v_log_f32_e32 v143, v124
	v_mul_f32_e64 v145, |v144|, s53
	v_fmac_f32_e32 v142, 0xbf317218, v133
	s_waitcnt lgkmcnt(0)
	v_mfma_f32_16x16x4_f32 v[124:127], v134, v165, v[128:131]
	s_nop 2
	v_exp_f32_e32 v128, v145
	v_min_f32_e32 v145, 0, v132
	ds_read2st64_b32 v[132:133], v136 offset0:12 offset1:13
	v_fmac_f32_e32 v145, 0xbf317218, v143
	v_add_f32_e32 v128, 1.0, v128
	v_log_f32_e32 v128, v128
	v_min_f32_e32 v143, 0, v144
	v_mfma_f32_16x16x4_f32 v[124:127], v135, v166, v[124:127]
	v_fmac_f32_e32 v143, 0xbf317218, v128
	s_nop 8
	v_add_f32_e32 v124, v167, v124
	v_mul_f32_e64 v128, |v124|, s53
	v_exp_f32_e32 v134, v128
	s_waitcnt lgkmcnt(0)
	v_mfma_f32_16x16x4_f32 v[128:131], v132, v155, 0
	v_add_f32_e32 v125, v167, v125
	v_mul_f32_e64 v135, |v125|, s53
	v_exp_f32_e32 v132, v135
	v_min_f32_e32 v144, 0, v124
	v_add_f32_e32 v124, 1.0, v134
	ds_read2st64_b32 v[134:135], v136 offset0:14 offset1:15
	v_add_f32_e32 v132, 1.0, v132
	v_mfma_f32_16x16x4_f32 v[128:131], v133, v164, v[128:131]
	v_log_f32_e32 v132, v132
	v_log_f32_e32 v124, v124
	v_min_f32_e32 v133, 0, v125
	v_add_f32_e32 v146, v167, v127
	v_fmac_f32_e32 v133, 0xbf317218, v132
	v_add_f32_e32 v132, v167, v126
	v_fmac_f32_e32 v144, 0xbf317218, v124
	v_mul_f32_e64 v124, |v132|, s53
	v_exp_f32_e32 v136, v124
	s_waitcnt lgkmcnt(0)
	v_mfma_f32_16x16x4_f32 v[124:127], v134, v165, v[128:131]
	v_mul_f32_e64 v128, |v146|, s53
	v_exp_f32_e32 v128, v128
	v_add_f32_e32 v130, 1.0, v136
	v_log_f32_e32 v130, v130
	v_min_f32_e32 v129, 0, v132
	v_add_f32_e32 v128, 1.0, v128
	v_log_f32_e32 v128, v128
	v_mfma_f32_16x16x4_f32 v[124:127], v135, v166, v[124:127]
	v_fmac_f32_e32 v129, 0xbf317218, v130
	v_min_f32_e32 v130, 0, v146
	v_fmac_f32_e32 v130, 0xbf317218, v128
	s_nop 6
	v_add_f32_e32 v124, v167, v124
	v_mul_f32_e64 v131, |v124|, s53
	v_exp_f32_e32 v131, v131
	v_add_f32_e32 v125, v167, v125
	v_min_f32_e32 v124, 0, v124
	v_add_f32_e32 v126, v167, v126
	v_add_f32_e32 v128, 1.0, v131
	v_mul_f32_e64 v131, |v125|, s53
	v_log_f32_e32 v128, v128
	v_exp_f32_e32 v131, v131
	v_add_f32_e32 v127, v167, v127
	v_mul_f32_e64 v132, |v127|, s53
	v_fmac_f32_e32 v124, 0xbf317218, v128
	v_add_f32_e32 v128, 1.0, v131
	v_mul_f32_e64 v131, |v126|, s53
	v_log_f32_e32 v128, v128
	v_exp_f32_e32 v131, v131
	v_exp_f32_e32 v132, v132
	v_min_f32_e32 v125, 0, v125
	v_fmac_f32_e32 v125, 0xbf317218, v128
	v_add_f32_e32 v128, 1.0, v131
	v_add_f32_e32 v131, 1.0, v132
	v_log_f32_e32 v131, v131
	v_log_f32_e32 v128, v128
	v_min_f32_e32 v127, 0, v127
	v_min_f32_e32 v126, 0, v126
	v_fmac_f32_e32 v127, 0xbf317218, v131
	v_fmac_f32_e32 v126, 0xbf317218, v128
	v_fma_f32 v127, v127, s54, 0
	v_fmamk_f32 v126, v126, 0x3d800000, v127
	v_fmamk_f32 v125, v125, 0x3d800000, v126
	v_fmamk_f32 v124, v124, 0x3d800000, v125
	v_fmamk_f32 v128, v130, 0x3d800000, v124
	v_fmamk_f32 v129, v129, 0x3d800000, v128
	v_fmamk_f32 v130, v133, 0x3d800000, v129
	v_fmamk_f32 v131, v144, 0x3d800000, v130
	v_fmamk_f32 v132, v143, 0x3d800000, v131
	v_fmamk_f32 v133, v145, 0x3d800000, v132
	v_fmamk_f32 v134, v142, 0x3d800000, v133
	v_fmamk_f32 v135, v141, 0x3d800000, v134
	v_fmamk_f32 v136, v140, 0x3d800000, v135
	v_fmamk_f32 v139, v139, 0x3d800000, v136
	v_fmamk_f32 v138, v138, 0x3d800000, v139
	v_fmamk_f32 v137, v137, 0x3d800000, v138
	ds_bpermute_b32 v140, v174, v137
	ds_bpermute_b32 v141, v173, v137
	ds_bpermute_b32 v142, v172, v137
	s_waitcnt lgkmcnt(2)
	v_cndmask_b32_e64 v140, v140, 0, s[2:3]
	s_waitcnt lgkmcnt(1)
	v_cndmask_b32_e64 v141, 0, v141, s[4:5]
	v_add_f32_e32 v140, v141, v140
	s_waitcnt lgkmcnt(0)
	v_cndmask_b32_e64 v141, 0, v142, s[6:7]
	v_add_f32_e32 v140, v141, v140
	v_add_f32_e32 v137, v140, v137
	v_add_f32_e32 v138, v140, v138
	v_add_f32_e32 v124, v140, v124
	v_add_f32_e32 v125, v140, v125
	ds_write2st64_b32 v184, v137, v138 offset0:24 offset1:26
	v_add_f32_e32 v137, v140, v139
	v_add_f32_e32 v136, v140, v136
	v_add_f32_e32 v135, v140, v135
	v_add_f32_e32 v134, v140, v134
	v_add_f32_e32 v133, v140, v133
	v_add_f32_e32 v132, v140, v132
	v_add_f32_e32 v131, v140, v131
	v_add_f32_e32 v130, v140, v130
	v_add_f32_e32 v129, v140, v129
	v_add_f32_e32 v128, v140, v128
	ds_write2st64_b32 v184, v124, v125 offset0:48 offset1:50
	v_add_f32_e32 v124, v140, v126
	v_add_f32_e32 v125, v140, v127
	ds_write2st64_b32 v184, v137, v136 offset0:28 offset1:30
	ds_write2st64_b32 v184, v135, v134 offset0:32 offset1:34
	ds_write2st64_b32 v184, v133, v132 offset0:36 offset1:38
	ds_write2st64_b32 v184, v131, v130 offset0:40 offset1:42
	ds_write2st64_b32 v184, v129, v128 offset0:44 offset1:46
	ds_write2st64_b32 v184, v124, v125 offset0:52 offset1:54
	s_waitcnt lgkmcnt(0)
	s_barrier
	s_and_saveexec_b64 s[0:1], s[8:9]
	s_cbranch_execz .LBB0_2185
	ds_read_b32 v124, v175 offset:6144
	v_lshl_add_u32 v125, s57, 9, v175
	s_waitcnt lgkmcnt(0)
	v_mul_f32_e32 v255, 0x3fb8aa3b, v124
	v_exp_f32_e32 v255, v255
	s_nop 0
	ds_write_b32 v125, v255 offset:4096

.LBB0_2267:
	s_add_u32 s62, s92, s74
	s_addc_u32 s63, s94, s75
	s_add_u32 s49, s53, s74
	s_addc_u32 s61, s55, s75
	v_lshl_add_u64 v[70:71], s[62:63], 0, v[112:113]
	s_add_u32 s62, s49, s0
	v_add_co_u32_e32 v74, vcc, s72, v70
	s_addc_u32 s63, s61, 0
	s_nop 0
	v_addc_co_u32_e32 v75, vcc, 0, v71, vcc
	v_lshl_add_u64 v[86:87], s[62:63], 0, v[114:115]
	v_add_co_u32_e32 v78, vcc, s81, v86
	s_and_b32 s49, s95, 1
	s_add_i32 s89, s1, 0xf0
	v_addc_co_u32_e32 v79, vcc, 0, v87, vcc
	s_cmp_eq_u32 s49, 0
	v_add_co_u32_e32 v82, vcc, s72, v86
	s_cselect_b64 s[76:77], -1, 0
	s_nop 0
	v_addc_co_u32_e32 v83, vcc, 0, v87, vcc
	s_and_b64 s[62:63], s[76:77], exec
	global_load_dwordx4 v[94:97], v[70:71], off
	global_load_dwordx4 v[98:101], v[70:71], off offset:1024
	s_nop 0
	global_load_dwordx4 v[70:73], v[74:75], off
	global_load_dwordx4 v[90:93], v[74:75], off offset:1024
	s_cselect_b32 s61, 0xf0, s89
	global_load_dwordx4 v[74:77], v[86:87], off
	v_add_co_u32_e32 v86, vcc, s73, v86
	v_and_b32_e32 v137, 63, v154
	v_lshl_add_u32 v137, v137, 2, s61
	s_nop 0
	v_addc_co_u32_e32 v87, vcc, 0, v87, vcc
	global_load_dwordx4 v[78:81], v[78:79], off
	s_nop 0
	global_load_dwordx4 v[82:85], v[82:83], off
	s_nop 0
	global_load_dwordx4 v[86:89], v[86:87], off
	ds_read2st64_b32 v[108:109], v137 offset1:1
	ds_read2st64_b32 v[142:143], v137 offset0:2 offset1:3
	s_waitcnt lgkmcnt(1)
	v_mfma_f32_16x16x4_f32 v[138:141], v108, v102, 0
	ds_read2st64_b32 v[146:147], v137 offset0:8 offset1:9
	v_mfma_f32_16x16x4_f32 v[138:141], v109, v103, v[138:141]
	s_waitcnt lgkmcnt(1)
	v_mfma_f32_16x16x4_f32 v[138:141], v142, v104, v[138:141]
	v_mfma_f32_16x16x4_f32 v[138:141], v143, v105, v[138:141]
	ds_read2st64_b32 v[142:143], v137 offset0:4 offset1:5
	s_nop 8
	v_add_f32_e32 v108, v106, v138
	v_min_f32_e32 v107, 0, v108
	v_mul_f32_e64 v108, |v108|, s66
	v_exp_f32_e32 v108, v108
	v_add_f32_e32 v109, v106, v139
	v_add_f32_e32 v135, v106, v140
	v_add_f32_e32 v138, v106, v141
	v_add_f32_e32 v108, 1.0, v108
	v_log_f32_e32 v108, v108
	s_nop 0
	v_fmac_f32_e32 v107, 0xbf317218, v108
	v_min_f32_e32 v108, 0, v109
	v_mul_f32_e64 v109, |v109|, s66
	v_exp_f32_e32 v109, v109
	v_fma_f32 v107, v107, s67, 0
	v_add_f32_e32 v109, 1.0, v109
	v_log_f32_e32 v109, v109
	s_nop 0
	v_fmac_f32_e32 v108, 0xbf317218, v109
	v_min_f32_e32 v109, 0, v135
	v_mul_f32_e64 v135, |v135|, s66
	v_exp_f32_e32 v135, v135
	v_fmamk_f32 v108, v108, 0x3d800000, v107
	v_add_f32_e32 v135, 1.0, v135
	v_log_f32_e32 v135, v135
	s_nop 0
	v_fmac_f32_e32 v109, 0xbf317218, v135
	v_min_f32_e32 v135, 0, v138
	v_mul_f32_e64 v138, |v138|, s66
	v_exp_f32_e32 v138, v138
	v_fmamk_f32 v109, v109, 0x3d800000, v108
	v_add_f32_e32 v138, 1.0, v138
	v_log_f32_e32 v138, v138
	s_nop 0
	v_fmac_f32_e32 v135, 0xbf317218, v138
	s_waitcnt lgkmcnt(0)
	v_mfma_f32_16x16x4_f32 v[138:141], v142, v102, 0
	v_fmamk_f32 v135, v135, 0x3d800000, v109
	v_mfma_f32_16x16x4_f32 v[138:141], v143, v103, v[138:141]
	ds_read2st64_b32 v[142:143], v137 offset0:6 offset1:7
	s_waitcnt lgkmcnt(0)
	v_mfma_f32_16x16x4_f32 v[138:141], v142, v104, v[138:141]
	v_mfma_f32_16x16x4_f32 v[138:141], v143, v105, v[138:141]
	s_nop 9
	v_add_f32_e32 v142, v106, v138
	v_min_f32_e32 v138, 0, v142
	v_mul_f32_e64 v142, |v142|, s66
	v_exp_f32_e32 v142, v142
	s_nop 0
	v_add_f32_e32 v142, 1.0, v142
	v_log_f32_e32 v142, v142
	s_nop 0
	v_fmac_f32_e32 v138, 0xbf317218, v142
	v_add_f32_e32 v142, v106, v139
	v_min_f32_e32 v139, 0, v142
	v_mul_f32_e64 v142, |v142|, s66
	v_exp_f32_e32 v142, v142
	s_nop 0
	v_add_f32_e32 v142, 1.0, v142
	v_log_f32_e32 v142, v142
	s_nop 0
	v_fmac_f32_e32 v139, 0xbf317218, v142
	v_add_f32_e32 v142, v106, v140
	v_min_f32_e32 v140, 0, v142
	v_mul_f32_e64 v142, |v142|, s66
	v_exp_f32_e32 v142, v142
	s_nop 0
	v_add_f32_e32 v142, 1.0, v142
	v_log_f32_e32 v142, v142
	s_nop 0
	v_fmac_f32_e32 v140, 0xbf317218, v142
	v_add_f32_e32 v142, v106, v141
	v_min_f32_e32 v141, 0, v142
	v_mul_f32_e64 v142, |v142|, s66
	v_exp_f32_e32 v142, v142
	s_nop 0
	v_add_f32_e32 v142, 1.0, v142
	v_log_f32_e32 v142, v142
	s_nop 0
	v_fmac_f32_e32 v141, 0xbf317218, v142
	v_mfma_f32_16x16x4_f32 v[142:145], v146, v102, 0
	v_mfma_f32_16x16x4_f32 v[142:145], v147, v103, v[142:145]
	ds_read2st64_b32 v[146:147], v137 offset0:10 offset1:11
	s_waitcnt lgkmcnt(0)
	v_mfma_f32_16x16x4_f32 v[142:145], v146, v104, v[142:145]
	v_mfma_f32_16x16x4_f32 v[142:145], v147, v105, v[142:145]
	ds_read2st64_b32 v[146:147], v137 offset0:12 offset1:13
	s_nop 8
	v_add_f32_e32 v142, v106, v142
	v_min_f32_e32 v148, 0, v142
	v_mul_f32_e64 v142, |v142|, s66
	v_exp_f32_e32 v142, v142
	s_nop 0
	v_add_f32_e32 v142, 1.0, v142
	v_log_f32_e32 v142, v142
	s_nop 0
	v_fmac_f32_e32 v148, 0xbf317218, v142
	v_add_f32_e32 v142, v106, v143
	v_min_f32_e32 v149, 0, v142
	v_mul_f32_e64 v142, |v142|, s66
	v_exp_f32_e32 v142, v142
	s_nop 0
	v_add_f32_e32 v142, 1.0, v142
	v_log_f32_e32 v142, v142
	s_nop 0
	v_fmac_f32_e32 v149, 0xbf317218, v142
	v_add_f32_e32 v142, v106, v144
	v_min_f32_e32 v150, 0, v142
	v_mul_f32_e64 v142, |v142|, s66
	v_exp_f32_e32 v142, v142
	s_nop 0
	v_add_f32_e32 v142, 1.0, v142
	v_log_f32_e32 v142, v142
	s_nop 0
	v_fmac_f32_e32 v150, 0xbf317218, v142
	v_add_f32_e32 v142, v106, v145
	v_min_f32_e32 v151, 0, v142
	v_mul_f32_e64 v142, |v142|, s66
	v_exp_f32_e32 v142, v142
	s_nop 0
	v_add_f32_e32 v142, 1.0, v142
	v_log_f32_e32 v142, v142
	s_nop 0
	v_fmac_f32_e32 v151, 0xbf317218, v142
	s_waitcnt lgkmcnt(0)
	v_mfma_f32_16x16x4_f32 v[142:145], v146, v102, 0
	v_mfma_f32_16x16x4_f32 v[142:145], v147, v103, v[142:145]
	ds_read2st64_b32 v[146:147], v137 offset0:14 offset1:15
	s_waitcnt lgkmcnt(0)
	v_mfma_f32_16x16x4_f32 v[142:145], v146, v104, v[142:145]
	v_mfma_f32_16x16x4_f32 v[142:145], v147, v105, v[142:145]
	s_nop 9
	v_add_f32_e32 v137, v106, v142
	v_min_f32_e32 v142, 0, v137
	v_mul_f32_e64 v137, |v137|, s66
	v_exp_f32_e32 v137, v137
	s_nop 0
	v_add_f32_e32 v137, 1.0, v137
	v_log_f32_e32 v137, v137
	s_nop 0
	v_fmac_f32_e32 v142, 0xbf317218, v137
	v_add_f32_e32 v137, v106, v143
	v_min_f32_e32 v143, 0, v137
	v_mul_f32_e64 v137, |v137|, s66
	v_exp_f32_e32 v137, v137
	s_nop 0
	v_add_f32_e32 v137, 1.0, v137
	v_log_f32_e32 v137, v137
	s_nop 0
	v_fmac_f32_e32 v143, 0xbf317218, v137
	v_add_f32_e32 v137, v106, v144
	v_min_f32_e32 v144, 0, v137
	v_mul_f32_e64 v137, |v137|, s66
	v_exp_f32_e32 v137, v137
	s_nop 0
	v_add_f32_e32 v137, 1.0, v137
	v_log_f32_e32 v137, v137
	s_nop 0
	v_fmac_f32_e32 v144, 0xbf317218, v137
	v_add_f32_e32 v137, v106, v145
	v_min_f32_e32 v145, 0, v137
	v_mul_f32_e64 v137, |v137|, s66
	v_exp_f32_e32 v137, v137
	s_nop 0
	v_add_f32_e32 v137, 1.0, v137
	v_log_f32_e32 v137, v137
	s_nop 0
	v_fmac_f32_e32 v145, 0xbf317218, v137
	v_fmamk_f32 v137, v138, 0x3d800000, v135
	v_fmamk_f32 v138, v139, 0x3d800000, v137
	v_fmamk_f32 v139, v140, 0x3d800000, v138
	v_fmamk_f32 v140, v141, 0x3d800000, v139
	v_fmamk_f32 v141, v148, 0x3d800000, v140
	v_fmamk_f32 v146, v149, 0x3d800000, v141
	v_fmamk_f32 v147, v150, 0x3d800000, v146
	v_fmamk_f32 v148, v151, 0x3d800000, v147
	v_fmamk_f32 v142, v142, 0x3d800000, v148
	v_fmamk_f32 v143, v143, 0x3d800000, v142
	v_fmamk_f32 v144, v144, 0x3d800000, v143
	v_fmamk_f32 v145, v145, 0x3d800000, v144
	ds_bpermute_b32 v149, v190, v145
	ds_bpermute_b32 v150, v191, v145
	ds_bpermute_b32 v151, v192, v145
	s_waitcnt lgkmcnt(2)
	v_cndmask_b32_e64 v149, v149, 0, s[4:5]
	s_waitcnt lgkmcnt(1)
	v_cndmask_b32_e64 v150, 0, v150, s[6:7]
	v_add_f32_e32 v149, v149, v150
	s_waitcnt lgkmcnt(0)
	v_cndmask_b32_e64 v150, 0, v151, s[8:9]
	v_add_f32_e32 v149, v149, v150
	v_add_f32_e32 v107, v107, v149
	v_add_f32_e32 v108, v108, v149
	ds_write2st64_b32 v204, v107, v108 offset0:24 offset1:26
	v_add_f32_e32 v107, v109, v149
	v_add_f32_e32 v108, v135, v149
	ds_write2st64_b32 v204, v107, v108 offset0:28 offset1:30
	v_add_f32_e32 v107, v137, v149
	v_add_f32_e32 v108, v138, v149
	ds_write2st64_b32 v204, v107, v108 offset0:32 offset1:34
	v_add_f32_e32 v107, v139, v149
	v_add_f32_e32 v108, v140, v149
	ds_write2st64_b32 v204, v107, v108 offset0:36 offset1:38
	v_add_f32_e32 v107, v141, v149
	v_add_f32_e32 v108, v146, v149
	ds_write2st64_b32 v204, v107, v108 offset0:40 offset1:42
	v_add_f32_e32 v107, v149, v147
	v_add_f32_e32 v108, v149, v148
	ds_write2st64_b32 v204, v107, v108 offset0:44 offset1:46
	v_add_f32_e32 v107, v149, v142
	v_add_f32_e32 v108, v149, v143
	ds_write2st64_b32 v204, v107, v108 offset0:48 offset1:50
	v_add_f32_e32 v107, v149, v144
	v_add_f32_e32 v108, v149, v145
	ds_write2st64_b32 v204, v107, v108 offset0:52 offset1:54
	s_waitcnt lgkmcnt(0)
	s_barrier
	s_and_saveexec_b64 s[62:63], s[10:11]
	s_cbranch_execz .LBB0_2269
	ds_read_b32 v107, v181 offset:38400
	v_lshl_add_u32 v108, s49, 9, v181
	s_waitcnt lgkmcnt(0)
	v_mul_f32_e32 v255, 0x3fb8aa3b, v107
	v_exp_f32_e32 v255, v255
	s_nop 0
	ds_write_b32 v108, v255 offset:4096

.LBB0_2283:
	s_add_u32 s60, s70, s58
	s_addc_u32 s61, s71, s59
	s_add_u32 s49, s64, s58
	s_addc_u32 s69, s65, s59
	s_add_u32 s53, s49, s0
	v_lshl_add_u64 v[70:71], s[60:61], 0, v[112:113]
	s_addc_u32 s61, s69, 0
	s_add_u32 s60, s53, 0xafc0800
	v_add_co_u32_e32 v74, vcc, s72, v70
	s_addc_u32 s61, s61, 0
	s_nop 0
	v_addc_co_u32_e32 v75, vcc, 0, v71, vcc
	v_lshl_add_u64 v[86:87], s[60:61], 0, v[114:115]
	v_add_co_u32_e32 v78, vcc, s81, v86
	s_and_b32 s68, s74, 1
	s_nop 0
	v_addc_co_u32_e32 v79, vcc, 0, v87, vcc
	s_cmp_eq_u32 s68, 0
	v_add_co_u32_e32 v82, vcc, s72, v86
	s_cselect_b64 s[60:61], -1, 0
	s_nop 0
	v_addc_co_u32_e32 v83, vcc, 0, v87, vcc
	s_and_b64 s[62:63], s[60:61], exec
	global_load_dwordx4 v[94:97], v[70:71], off
	global_load_dwordx4 v[98:101], v[70:71], off offset:1024
	s_nop 0
	global_load_dwordx4 v[70:73], v[74:75], off
	global_load_dwordx4 v[90:93], v[74:75], off offset:1024
	s_cselect_b32 s53, 0xf0, s89
	global_load_dwordx4 v[74:77], v[86:87], off
	v_add_co_u32_e32 v86, vcc, s73, v86
	v_and_b32_e32 v105, 63, v154
	v_lshl_add_u32 v105, v105, 2, s53
	s_nop 0
	v_addc_co_u32_e32 v87, vcc, 0, v87, vcc
	global_load_dwordx4 v[78:81], v[78:79], off
	s_nop 0
	global_load_dwordx4 v[82:85], v[82:83], off
	s_nop 0
	global_load_dwordx4 v[86:89], v[86:87], off
	ds_read2st64_b32 v[102:103], v105 offset1:1
	ds_read2st64_b32 v[140:141], v105 offset0:2 offset1:3
	s_waitcnt vmcnt(12) lgkmcnt(1)
	v_mfma_f32_16x16x4_f32 v[106:109], v102, v223, 0
	ds_read2st64_b32 v[144:145], v105 offset0:8 offset1:9
	s_waitcnt vmcnt(11)
	v_mfma_f32_16x16x4_f32 v[106:109], v103, v224, v[106:109]
	s_waitcnt vmcnt(10) lgkmcnt(1)
	v_mfma_f32_16x16x4_f32 v[106:109], v140, v225, v[106:109]
	s_waitcnt vmcnt(9)
	v_mfma_f32_16x16x4_f32 v[106:109], v141, v226, v[106:109]
	ds_read2st64_b32 v[140:141], v105 offset0:4 offset1:5
	s_waitcnt vmcnt(8)
	s_nop 7
	v_add_f32_e32 v102, v227, v106
	v_min_f32_e32 v0, 0, v102
	v_mul_f32_e64 v102, |v102|, s66
	v_exp_f32_e32 v102, v102
	v_add_f32_e32 v103, v227, v107
	v_add_f32_e32 v104, v227, v108
	v_add_f32_e32 v106, v227, v109
	v_add_f32_e32 v102, 1.0, v102
	v_log_f32_e32 v102, v102
	s_nop 0
	v_fmac_f32_e32 v0, 0xbf317218, v102
	v_min_f32_e32 v102, 0, v103
	v_mul_f32_e64 v103, |v103|, s66
	v_exp_f32_e32 v103, v103
	s_nop 0
	v_add_f32_e32 v103, 1.0, v103
	v_log_f32_e32 v103, v103
	s_nop 0
	v_fmac_f32_e32 v102, 0xbf317218, v103
	v_min_f32_e32 v103, 0, v104
	v_mul_f32_e64 v104, |v104|, s66
	v_exp_f32_e32 v104, v104
	s_nop 0
	v_add_f32_e32 v104, 1.0, v104
	v_log_f32_e32 v104, v104
	s_nop 0
	v_fmac_f32_e32 v103, 0xbf317218, v104
	v_min_f32_e32 v104, 0, v106
	v_mul_f32_e64 v106, |v106|, s66
	v_exp_f32_e32 v106, v106
	s_nop 0
	v_add_f32_e32 v106, 1.0, v106
	v_log_f32_e32 v106, v106
	s_nop 0
	v_fmac_f32_e32 v104, 0xbf317218, v106
	s_waitcnt lgkmcnt(0)
	v_mfma_f32_16x16x4_f32 v[106:109], v140, v223, 0
	v_mfma_f32_16x16x4_f32 v[106:109], v141, v224, v[106:109]
	ds_read2st64_b32 v[140:141], v105 offset0:6 offset1:7
	s_waitcnt lgkmcnt(0)
	v_mfma_f32_16x16x4_f32 v[106:109], v140, v225, v[106:109]
	v_mfma_f32_16x16x4_f32 v[106:109], v141, v226, v[106:109]
	v_mfma_f32_16x16x4_f32 v[140:143], v144, v223, 0
	s_nop 8
	v_add_f32_e32 v135, v227, v106
	v_min_f32_e32 v106, 0, v135
	v_mul_f32_e64 v135, |v135|, s66
	v_exp_f32_e32 v135, v135
	s_nop 0
	v_add_f32_e32 v135, 1.0, v135
	v_log_f32_e32 v135, v135
	v_mfma_f32_16x16x4_f32 v[140:143], v145, v224, v[140:143]
	ds_read2st64_b32 v[144:145], v105 offset0:10 offset1:11
	v_fmac_f32_e32 v106, 0xbf317218, v135
	v_add_f32_e32 v135, v227, v107
	v_min_f32_e32 v107, 0, v135
	v_mul_f32_e64 v135, |v135|, s66
	v_exp_f32_e32 v135, v135
	s_waitcnt lgkmcnt(0)
	v_mfma_f32_16x16x4_f32 v[140:143], v144, v225, v[140:143]
	v_add_f32_e32 v135, 1.0, v135
	v_log_f32_e32 v135, v135
	s_nop 0
	v_fmac_f32_e32 v107, 0xbf317218, v135
	v_add_f32_e32 v135, v227, v108
	v_min_f32_e32 v108, 0, v135
	v_mul_f32_e64 v135, |v135|, s66
	v_exp_f32_e32 v135, v135
	v_mfma_f32_16x16x4_f32 v[140:143], v145, v226, v[140:143]
	ds_read2st64_b32 v[144:145], v105 offset0:12 offset1:13
	v_add_f32_e32 v135, 1.0, v135
	v_log_f32_e32 v135, v135
	s_nop 0
	v_fmac_f32_e32 v108, 0xbf317218, v135
	v_add_f32_e32 v135, v227, v109
	v_min_f32_e32 v109, 0, v135
	v_mul_f32_e64 v135, |v135|, s66
	v_exp_f32_e32 v135, v135
	s_nop 0
	v_add_f32_e32 v135, 1.0, v135
	v_log_f32_e32 v135, v135
	s_nop 0
	v_fmac_f32_e32 v109, 0xbf317218, v135
	v_add_f32_e32 v135, v227, v140
	v_min_f32_e32 v137, 0, v135
	v_mul_f32_e64 v135, |v135|, s66
	v_exp_f32_e32 v135, v135
	s_nop 0
	v_add_f32_e32 v135, 1.0, v135
	v_log_f32_e32 v135, v135
	s_nop 0
	v_fmac_f32_e32 v137, 0xbf317218, v135
	v_add_f32_e32 v135, v227, v141
	v_min_f32_e32 v146, 0, v135
	v_mul_f32_e64 v135, |v135|, s66
	v_exp_f32_e32 v135, v135
	s_nop 0
	v_add_f32_e32 v135, 1.0, v135
	v_log_f32_e32 v135, v135
	s_nop 0
	v_fmac_f32_e32 v146, 0xbf317218, v135
	v_add_f32_e32 v135, v227, v142
	v_min_f32_e32 v147, 0, v135
	v_mul_f32_e64 v135, |v135|, s66
	v_exp_f32_e32 v135, v135
	s_nop 0
	v_add_f32_e32 v135, 1.0, v135
	v_log_f32_e32 v135, v135
	s_nop 0
	v_fmac_f32_e32 v147, 0xbf317218, v135
	v_add_f32_e32 v135, v227, v143
	s_waitcnt lgkmcnt(0)
	v_mfma_f32_16x16x4_f32 v[140:143], v144, v223, 0
	v_min_f32_e32 v148, 0, v135
	v_mul_f32_e64 v135, |v135|, s66
	v_exp_f32_e32 v135, v135
	s_nop 0
	v_add_f32_e32 v135, 1.0, v135
	v_mfma_f32_16x16x4_f32 v[140:143], v145, v224, v[140:143]
	ds_read2st64_b32 v[144:145], v105 offset0:14 offset1:15
	v_log_f32_e32 v135, v135
	s_nop 0
	v_fmac_f32_e32 v148, 0xbf317218, v135
	s_waitcnt lgkmcnt(0)
	v_mfma_f32_16x16x4_f32 v[140:143], v144, v225, v[140:143]
	v_mfma_f32_16x16x4_f32 v[140:143], v145, v226, v[140:143]
	s_nop 9
	v_add_f32_e32 v105, v227, v140
	v_min_f32_e32 v135, 0, v105
	v_mul_f32_e64 v105, |v105|, s66
	v_exp_f32_e32 v105, v105
	s_nop 0
	v_add_f32_e32 v105, 1.0, v105
	v_log_f32_e32 v105, v105
	s_nop 0
	v_fmac_f32_e32 v135, 0xbf317218, v105
	v_add_f32_e32 v105, v227, v141
	v_min_f32_e32 v140, 0, v105
	v_mul_f32_e64 v105, |v105|, s66
	v_exp_f32_e32 v105, v105
	s_nop 0
	v_add_f32_e32 v105, 1.0, v105
	v_log_f32_e32 v105, v105
	s_nop 0
	v_fmac_f32_e32 v140, 0xbf317218, v105
	v_add_f32_e32 v105, v227, v142
	v_min_f32_e32 v141, 0, v105
	v_mul_f32_e64 v105, |v105|, s66
	v_exp_f32_e32 v105, v105
	s_nop 0
	v_add_f32_e32 v105, 1.0, v105
	v_log_f32_e32 v105, v105
	s_nop 0
	v_fmac_f32_e32 v141, 0xbf317218, v105
	v_add_f32_e32 v105, v227, v143
	v_min_f32_e32 v142, 0, v105
	v_mul_f32_e64 v105, |v105|, s66
	v_exp_f32_e32 v105, v105
	s_nop 0
	v_add_f32_e32 v105, 1.0, v105
	v_log_f32_e32 v105, v105
	s_nop 0
	v_fmac_f32_e32 v142, 0xbf317218, v105
	v_fma_f32 v105, v142, s67, 0
	v_fmamk_f32 v141, v141, 0x3d800000, v105
	v_fmamk_f32 v140, v140, 0x3d800000, v141
	v_fmamk_f32 v135, v135, 0x3d800000, v140
	v_fmamk_f32 v142, v148, 0x3d800000, v135
	v_fmamk_f32 v143, v147, 0x3d800000, v142
	v_fmamk_f32 v144, v146, 0x3d800000, v143
	v_fmamk_f32 v137, v137, 0x3d800000, v144
	v_fmamk_f32 v109, v109, 0x3d800000, v137
	v_fmamk_f32 v108, v108, 0x3d800000, v109
	v_fmamk_f32 v107, v107, 0x3d800000, v108
	v_fmamk_f32 v106, v106, 0x3d800000, v107
	v_fmamk_f32 v104, v104, 0x3d800000, v106
	v_fmamk_f32 v103, v103, 0x3d800000, v104
	v_fmamk_f32 v102, v102, 0x3d800000, v103
	v_fmamk_f32 v0, v0, 0x3d800000, v102
	ds_bpermute_b32 v146, v192, v0
	ds_bpermute_b32 v147, v193, v0
	ds_bpermute_b32 v145, v191, v0
	s_waitcnt lgkmcnt(2)
	v_cndmask_b32_e64 v146, 0, v146, s[28:29]
	s_waitcnt lgkmcnt(1)
	v_cndmask_b32_e64 v147, v147, 0, s[8:9]
	v_add_f32_e32 v146, v146, v147
	s_waitcnt lgkmcnt(0)
	v_cndmask_b32_e64 v145, 0, v145, s[4:5]
	v_add_f32_e32 v145, v145, v146
	v_add_f32_e32 v0, v145, v0
	v_add_f32_e32 v102, v145, v102
	ds_write2st64_b32 v204, v0, v102 offset0:24 offset1:26
	v_add_f32_e32 v0, v145, v103
	v_add_f32_e32 v102, v145, v104
	ds_write2st64_b32 v204, v0, v102 offset0:28 offset1:30
	v_add_f32_e32 v0, v145, v106
	v_add_f32_e32 v102, v145, v107
	ds_write2st64_b32 v204, v0, v102 offset0:32 offset1:34
	v_add_f32_e32 v0, v145, v108
	v_add_f32_e32 v102, v145, v109
	ds_write2st64_b32 v204, v0, v102 offset0:36 offset1:38
	v_add_f32_e32 v0, v145, v137
	v_add_f32_e32 v102, v145, v144
	ds_write2st64_b32 v204, v0, v102 offset0:40 offset1:42
	v_add_f32_e32 v0, v145, v143
	v_add_f32_e32 v102, v145, v142
	ds_write2st64_b32 v204, v0, v102 offset0:44 offset1:46
	v_add_f32_e32 v0, v145, v135
	v_add_f32_e32 v102, v145, v140
	ds_write2st64_b32 v204, v0, v102 offset0:48 offset1:50
	v_add_f32_e32 v0, v145, v141
	v_add_f32_e32 v102, v145, v105
	ds_write2st64_b32 v204, v0, v102 offset0:52 offset1:54
	s_waitcnt lgkmcnt(0)
	s_barrier
	s_and_saveexec_b64 s[62:63], s[10:11]
	s_cbranch_execz .LBB0_2285
	ds_read_b32 v0, v181 offset:6144
	v_lshl_add_u32 v102, s68, 9, v181
	s_waitcnt lgkmcnt(0)
	v_mul_f32_e32 v255, 0x3fb8aa3b, v0
	v_exp_f32_e32 v255, v255
	s_nop 0
	ds_write_b32 v102, v255 offset:4096
